# mixer C step 2: bias and gate loads of each 16-row tile prefetched before its MFMA loop (no store-draining waits in the epilogue); MFMA loop reads its four LDS operands together and prefetches the nex
# baseline (speedup 1.0000x reference)
.LBB0_1094:
	s_add_i32 s6, s4, s19
	v_lshl_or_b32 v73, s6, 4, v21
	v_add_u32_e32 v74, s20, v73
	v_mov_b32_e32 v75, 0
	v_lshl_add_u64 v[74:75], v[74:75], 2, s[0:1]
	global_load_dword v72, v[74:75], off
	v_add_u32_e32 v73, s2, v73
	v_mov_b64_e32 v[74:75], s[14:15]
	v_mad_i64_i32 v[74:75], s[6:7], v73, s69, v[74:75]
	s_mov_b64 s[6:7], 0x7900e00
	v_mov_b32_e32 v76, v32
	v_mov_b32_e32 v77, 0
	v_lshl_add_u64 v[74:75], v[74:75], 0, s[6:7]
	s_nop 0
	v_lshl_add_u64 v[74:75], v[74:75], 0, v[76:77]
	global_load_dwordx2 v[64:65], v[74:75], off
	global_load_dwordx2 v[66:67], v[74:75], off offset:32
	global_load_dwordx2 v[68:69], v[74:75], off offset:64
	global_load_dwordx2 v[70:71], v[74:75], off offset:96
	s_lshr_b32 s6, s5, 5
	v_mov_b32_e32 v16, 0
	s_add_i32 s6, s6, 1
	v_mov_b64_e32 v[42:43], v[40:41]
	v_mov_b32_e32 v2, v58
	v_mov_b32_e32 v17, v16
	v_mov_b32_e32 v18, v16
	v_mov_b32_e32 v19, v16
	v_mov_b32_e32 v12, v16
	v_mov_b32_e32 v13, v16
	v_mov_b32_e32 v14, v16
	v_mov_b32_e32 v15, v16
	v_mov_b32_e32 v8, v16
	v_mov_b32_e32 v9, v16
	v_mov_b32_e32 v10, v16
	v_mov_b32_e32 v11, v16
	v_mov_b32_e32 v4, v16
	v_mov_b32_e32 v5, v16
	v_mov_b32_e32 v6, v16
	v_mov_b32_e32 v7, v16
	global_load_dwordx4 v[44:47], v[42:43], off
	v_lshl_add_u64 v[42:43], v[42:43], 0, 64
.LBB0_1095:
	ds_read_b128 v[48:51], v2
	ds_read_b128 v[78:81], v2 offset:4352
	ds_read_b128 v[82:85], v2 offset:8704
	ds_read_b128 v[86:89], v2 offset:13056
	s_add_i32 s6, s6, -1
	v_add_u32_e32 v2, 64, v2
	s_cmp_eq_u32 s6, 0
	s_waitcnt vmcnt(0)
	v_mov_b32_e32 v90, v44
	v_mov_b32_e32 v91, v45
	v_mov_b32_e32 v92, v46
	v_mov_b32_e32 v93, v47
	s_cbranch_scc1 .Lmc_ks_last
	global_load_dwordx4 v[44:47], v[42:43], off
	v_lshl_add_u64 v[42:43], v[42:43], 0, 64
.Lmc_ks_last:
	s_waitcnt lgkmcnt(3)
	v_mfma_f32_16x16x32_bf16 v[16:19], v[48:51], v[90:93], v[16:19]
	s_waitcnt lgkmcnt(2)
	v_mfma_f32_16x16x32_bf16 v[12:15], v[78:81], v[90:93], v[12:15]
	s_waitcnt lgkmcnt(1)
	v_mfma_f32_16x16x32_bf16 v[8:11], v[82:85], v[90:93], v[8:11]
	s_waitcnt lgkmcnt(0)
	v_mfma_f32_16x16x32_bf16 v[4:7], v[86:89], v[90:93], v[4:7]
	s_cbranch_scc0 .LBB0_1095
	s_add_i32 s6, s4, s19
	v_lshl_or_b32 v33, s6, 4, v21
	v_add_u32_e32 v2, s20, v33
	v_lshl_add_u64 v[42:43], v[2:3], 2, s[0:1]
	v_mov_b32_e32 v2, v72
	v_add_u32_e32 v33, s2, v33
	v_mov_b64_e32 v[42:43], s[14:15]
	v_mad_i64_i32 v[42:43], s[6:7], v33, s69, v[42:43]
	s_mov_b64 s[6:7], 0x7900e00
	s_nop 0
	v_lshl_add_u64 v[44:45], v[42:43], 0, s[6:7]
	s_movk_i32 s6, 0xf600
	v_mad_i64_i32 v[42:43], s[6:7], v33, s6, v[42:43]
	v_mov_b32_e32 v33, v3
	v_lshl_add_u64 v[46:47], v[44:45], 0, v[32:33]
	v_mov_b32_e32 v46, v64
	v_mov_b32_e32 v47, v65
	s_mov_b64 s[6:7], 0x18d00600
	v_lshl_add_u64 v[42:43], v[42:43], 0, s[6:7]
	v_mov_b32_e32 v39, v3
	s_add_i32 s4, s4, 1
	s_add_i32 s5, s5, 16
	s_mov_b64 s[6:7], 0x1000
	v_lshl_add_u64 v[40:41], v[40:41], 0, s[6:7]
	s_cmp_eq_u32 s4, s3
	v_add_f32_e32 v16, v2, v16
	v_add_f32_e32 v17, v2, v17
	v_add_f32_e32 v18, v2, v18
	v_add_f32_e32 v19, v2, v19
	v_add_f32_e32 v12, v2, v12
	v_add_f32_e32 v13, v2, v13
	v_add_f32_e32 v14, v2, v14
	v_add_f32_e32 v15, v2, v15
	v_add_f32_e32 v8, v2, v8
	v_add_f32_e32 v9, v2, v9
	v_add_f32_e32 v10, v2, v10
	v_add_f32_e32 v11, v2, v11
	v_lshlrev_b32_e32 v35, 16, v46
	v_mul_f32_e32 v37, 0x3d372713, v35
	v_mul_f32_e32 v37, v37, v35
	v_fma_f32 v37, v37, v35, v35
	v_mul_f32_e32 v37, 0x3f4c422a, v37
	v_add_f32_e32 v37, v37, v37
	v_mul_f32_e32 v37, 0xbfb8aa3b, v37
	v_exp_f32_e32 v37, v37
	v_add_f32_e32 v4, v2, v4
	v_add_f32_e32 v5, v2, v5
	v_add_f32_e32 v6, v2, v6
	v_add_f32_e32 v37, 1.0, v37
	v_rcp_f32_e32 v37, v37
	v_add_f32_e32 v2, v2, v7
	v_mul_f32_e32 v35, v37, v35
	v_mul_f32_e32 v16, v16, v35
	v_and_b32_e32 v35, 0xffff0000, v46
	v_mul_f32_e32 v37, 0x3d372713, v35
	v_mul_f32_e32 v37, v37, v35
	v_fma_f32 v37, v37, v35, v35
	v_mul_f32_e32 v37, 0x3f4c422a, v37
	v_add_f32_e32 v37, v37, v37
	v_mul_f32_e32 v37, 0xbfb8aa3b, v37
	v_exp_f32_e32 v37, v37
	s_nop 0
	v_add_f32_e32 v37, 1.0, v37
	v_rcp_f32_e32 v37, v37
	s_nop 0
	v_mul_f32_e32 v35, v37, v35
	v_mul_f32_e32 v17, v17, v35
	v_cvt_pk_bf16_f32 v16, v16, v17
	v_lshlrev_b32_e32 v17, 16, v47
	v_mul_f32_e32 v35, 0x3d372713, v17
	v_mul_f32_e32 v35, v35, v17
	v_fma_f32 v35, v35, v17, v17
	v_mul_f32_e32 v35, 0x3f4c422a, v35
	v_add_f32_e32 v35, v35, v35
	v_mul_f32_e32 v35, 0xbfb8aa3b, v35
	v_exp_f32_e32 v35, v35
	v_mov_b32_e32 v37, v3
	v_add_f32_e32 v35, 1.0, v35
	v_rcp_f32_e32 v35, v35
	s_nop 0
	v_mul_f32_e32 v17, v35, v17
	v_mul_f32_e32 v17, v18, v17
	v_and_b32_e32 v18, 0xffff0000, v47
	v_mul_f32_e32 v35, 0x3d372713, v18
	v_mul_f32_e32 v35, v35, v18
	v_fma_f32 v35, v35, v18, v18
	v_mul_f32_e32 v35, 0x3f4c422a, v35
	v_add_f32_e32 v35, v35, v35
	v_mul_f32_e32 v35, 0xbfb8aa3b, v35
	v_exp_f32_e32 v35, v35
	s_nop 0
	v_add_f32_e32 v35, 1.0, v35
	v_rcp_f32_e32 v35, v35
	s_nop 0
	v_mul_f32_e32 v18, v35, v18
	v_mul_f32_e32 v18, v19, v18
	v_cvt_pk_bf16_f32 v17, v17, v18
	v_lshl_add_u64 v[18:19], v[42:43], 0, v[32:33]
	v_mov_b32_e32 v35, v3
	global_store_dwordx2 v[18:19], v[16:17], off
	v_mov_b32_e32 v16, v66
	v_mov_b32_e32 v17, v67
	v_lshlrev_b32_e32 v18, 16, v16
	v_mul_f32_e32 v19, 0x3d372713, v18
	v_mul_f32_e32 v19, v19, v18
	v_fma_f32 v19, v19, v18, v18
	v_mul_f32_e32 v19, 0x3f4c422a, v19
	v_add_f32_e32 v19, v19, v19
	v_mul_f32_e32 v19, 0xbfb8aa3b, v19
	v_exp_f32_e32 v19, v19
	v_and_b32_e32 v16, 0xffff0000, v16
	v_add_f32_e32 v19, 1.0, v19
	v_rcp_f32_e32 v19, v19
	s_nop 0
	v_mul_f32_e32 v18, v19, v18
	v_mul_f32_e32 v12, v12, v18
	v_mul_f32_e32 v18, 0x3d372713, v16
	v_mul_f32_e32 v18, v18, v16
	v_fma_f32 v18, v18, v16, v16
	v_mul_f32_e32 v18, 0x3f4c422a, v18
	v_add_f32_e32 v18, v18, v18
	v_mul_f32_e32 v18, 0xbfb8aa3b, v18
	v_exp_f32_e32 v18, v18
	s_nop 0
	v_add_f32_e32 v18, 1.0, v18
	v_rcp_f32_e32 v18, v18
	s_nop 0
	v_mul_f32_e32 v16, v18, v16
	v_mul_f32_e32 v13, v13, v16
	v_cvt_pk_bf16_f32 v12, v12, v13
	v_lshlrev_b32_e32 v13, 16, v17
	v_mul_f32_e32 v16, 0x3d372713, v13
	v_mul_f32_e32 v16, v16, v13
	v_fma_f32 v16, v16, v13, v13
	v_mul_f32_e32 v16, 0x3f4c422a, v16
	v_add_f32_e32 v16, v16, v16
	v_mul_f32_e32 v16, 0xbfb8aa3b, v16
	v_exp_f32_e32 v16, v16
	s_nop 0
	v_add_f32_e32 v16, 1.0, v16
	v_rcp_f32_e32 v16, v16
	s_nop 0
	v_mul_f32_e32 v13, v16, v13
	v_mul_f32_e32 v13, v14, v13
	v_and_b32_e32 v14, 0xffff0000, v17
	v_mul_f32_e32 v16, 0x3d372713, v14
	v_mul_f32_e32 v16, v16, v14
	v_fma_f32 v16, v16, v14, v14
	v_mul_f32_e32 v16, 0x3f4c422a, v16
	v_add_f32_e32 v16, v16, v16
	v_mul_f32_e32 v16, 0xbfb8aa3b, v16
	v_exp_f32_e32 v16, v16
	s_nop 0
	v_add_f32_e32 v16, 1.0, v16
	v_rcp_f32_e32 v16, v16
	s_nop 0
	v_mul_f32_e32 v14, v16, v14
	v_mul_f32_e32 v14, v15, v14
	v_cvt_pk_bf16_f32 v13, v13, v14
	v_lshl_add_u64 v[14:15], v[42:43], 0, v[34:35]
	global_store_dwordx2 v[14:15], v[12:13], off
	v_mov_b32_e32 v12, v68
	v_mov_b32_e32 v13, v69
	v_lshlrev_b32_e32 v14, 16, v12
	v_mul_f32_e32 v15, 0x3d372713, v14
	v_mul_f32_e32 v15, v15, v14
	v_fma_f32 v15, v15, v14, v14
	v_mul_f32_e32 v15, 0x3f4c422a, v15
	v_add_f32_e32 v15, v15, v15
	v_mul_f32_e32 v15, 0xbfb8aa3b, v15
	v_exp_f32_e32 v15, v15
	v_and_b32_e32 v12, 0xffff0000, v12
	v_add_f32_e32 v15, 1.0, v15
	v_rcp_f32_e32 v15, v15
	s_nop 0
	v_mul_f32_e32 v14, v15, v14
	v_mul_f32_e32 v8, v8, v14
	v_mul_f32_e32 v14, 0x3d372713, v12
	v_mul_f32_e32 v14, v14, v12
	v_fma_f32 v14, v14, v12, v12
	v_mul_f32_e32 v14, 0x3f4c422a, v14
	v_add_f32_e32 v14, v14, v14
	v_mul_f32_e32 v14, 0xbfb8aa3b, v14
	v_exp_f32_e32 v14, v14
	s_nop 0
	v_add_f32_e32 v14, 1.0, v14
	v_rcp_f32_e32 v14, v14
	s_nop 0
	v_mul_f32_e32 v12, v14, v12
	v_mul_f32_e32 v9, v9, v12
	v_cvt_pk_bf16_f32 v8, v8, v9
	v_lshlrev_b32_e32 v9, 16, v13
	v_mul_f32_e32 v12, 0x3d372713, v9
	v_mul_f32_e32 v12, v12, v9
	v_fma_f32 v12, v12, v9, v9
	v_mul_f32_e32 v12, 0x3f4c422a, v12
	v_add_f32_e32 v12, v12, v12
	v_mul_f32_e32 v12, 0xbfb8aa3b, v12
	v_exp_f32_e32 v12, v12
	s_nop 0
	v_add_f32_e32 v12, 1.0, v12
	v_rcp_f32_e32 v12, v12
	s_nop 0
	v_mul_f32_e32 v9, v12, v9
	v_mul_f32_e32 v9, v10, v9
	v_and_b32_e32 v10, 0xffff0000, v13
	v_mul_f32_e32 v12, 0x3d372713, v10
	v_mul_f32_e32 v12, v12, v10
	v_fma_f32 v12, v12, v10, v10
	v_mul_f32_e32 v12, 0x3f4c422a, v12
	v_add_f32_e32 v12, v12, v12
	v_mul_f32_e32 v12, 0xbfb8aa3b, v12
	v_exp_f32_e32 v12, v12
	s_nop 0
	v_add_f32_e32 v12, 1.0, v12
	v_rcp_f32_e32 v12, v12
	s_nop 0
	v_mul_f32_e32 v10, v12, v10
	v_mul_f32_e32 v10, v11, v10
	v_cvt_pk_bf16_f32 v9, v9, v10
	v_lshl_add_u64 v[10:11], v[42:43], 0, v[36:37]
	global_store_dwordx2 v[10:11], v[8:9], off
	v_mov_b32_e32 v8, v70
	v_mov_b32_e32 v9, v71
	v_lshlrev_b32_e32 v10, 16, v8
	v_mul_f32_e32 v11, 0x3d372713, v10
	v_mul_f32_e32 v11, v11, v10
	v_fma_f32 v11, v11, v10, v10
	v_mul_f32_e32 v11, 0x3f4c422a, v11
	v_add_f32_e32 v11, v11, v11
	v_mul_f32_e32 v11, 0xbfb8aa3b, v11
	v_exp_f32_e32 v11, v11
	v_and_b32_e32 v8, 0xffff0000, v8
	v_add_f32_e32 v11, 1.0, v11
	v_rcp_f32_e32 v11, v11
	s_nop 0
	v_mul_f32_e32 v10, v11, v10
	v_mul_f32_e32 v4, v4, v10
	v_mul_f32_e32 v10, 0x3d372713, v8
	v_mul_f32_e32 v10, v10, v8
	v_fma_f32 v10, v10, v8, v8
	v_mul_f32_e32 v10, 0x3f4c422a, v10
	v_add_f32_e32 v10, v10, v10
	v_mul_f32_e32 v10, 0xbfb8aa3b, v10
	v_exp_f32_e32 v10, v10
	s_nop 0
	v_add_f32_e32 v10, 1.0, v10
	v_rcp_f32_e32 v10, v10
	s_nop 0
	v_mul_f32_e32 v8, v10, v8
	v_mul_f32_e32 v5, v5, v8
	v_cvt_pk_bf16_f32 v4, v4, v5
	v_lshlrev_b32_e32 v5, 16, v9
	v_mul_f32_e32 v8, 0x3d372713, v5
	v_mul_f32_e32 v8, v8, v5
	v_fma_f32 v8, v8, v5, v5
	v_mul_f32_e32 v8, 0x3f4c422a, v8
	v_add_f32_e32 v8, v8, v8
	v_mul_f32_e32 v8, 0xbfb8aa3b, v8
	v_exp_f32_e32 v8, v8
	s_nop 0
	v_add_f32_e32 v8, 1.0, v8
	v_rcp_f32_e32 v8, v8
	s_nop 0
	v_mul_f32_e32 v5, v8, v5
	v_mul_f32_e32 v5, v6, v5
	v_and_b32_e32 v6, 0xffff0000, v9
	v_mul_f32_e32 v8, 0x3d372713, v6
	v_mul_f32_e32 v8, v8, v6
	v_fma_f32 v8, v8, v6, v6
	v_mul_f32_e32 v8, 0x3f4c422a, v8
	v_add_f32_e32 v8, v8, v8
	v_mul_f32_e32 v8, 0xbfb8aa3b, v8
	v_exp_f32_e32 v8, v8
	s_nop 0
	v_add_f32_e32 v8, 1.0, v8
	v_rcp_f32_e32 v8, v8
	s_nop 0
	v_mul_f32_e32 v6, v8, v6
	v_mul_f32_e32 v2, v2, v6
	v_lshl_add_u64 v[6:7], v[42:43], 0, v[38:39]
	v_cvt_pk_bf16_f32 v5, v5, v2
	global_store_dwordx2 v[6:7], v[4:5], off
	s_cbranch_scc0 .LBB0_1094
	s_branch .LBB0_1087
